# HGRN2 read-out loop processes two iterations per trip with both iterations loads issued before the first is consumed
# baseline (speedup 1.0000x reference)
; DI size_t oix(int dir, int tok, int h, int v) { return (((size_t)(dir * 16 + h)) * NLAT + (size_t)tok) * 128 + (size_t)v; }
; DI size_t pix(int row, int col) { return ((size_t)(col >> 8) * MROWS + (size_t)row) * 256 + (size_t)(col & 255); }
; DI float bflo(unsigned w) { return __uint_as_float(w << 16); }
; DI float bfhi(unsigned w) { return __uint_as_float(w & 0xffff0000u); }
; DI unsigned cvt_pk_bf16(float lo, float hi) { unsigned r; asm volatile("v_cvt_pk_bf16_f32 %0, %1, %2" : "=v"(r) : "v"(lo), "v"(hi)); return r; }
; DI float siluf_(float v) { return v * __builtin_amdgcn_rcpf(1.0f + __expf(-v)); }
; DI void phase_readout(const Params& p) {
;     ...
;     for (int idx = blockIdx.x * NTHREADS + threadIdx.x; idx < total; idx += gridDim.x * NTHREADS) {
;         const int tok = idx >> 8, col = (idx & 255) * 8;
;         const u32x4 af = *(const u32x4*)(O + oix(0, tok, col >> 7, col & 127)), ab = *(const u32x4*)(O + oix(1, tok, col >> 7, col & 127));
;         const f32x4 o0 = (f32x4){bflo(af.x) + bflo(ab.x), bfhi(af.x) + bfhi(ab.x), bflo(af.y) + bflo(ab.y), bfhi(af.y) + bfhi(ab.y)};
;         const f32x4 o1 = (f32x4){bflo(af.z) + bflo(ab.z), bfhi(af.z) + bfhi(ab.z), bflo(af.w) + bflo(ab.w), bfhi(af.w) + bfhi(ab.w)};
;         float ss = (o0[0] * o0[0] + o0[1] * o0[1]) + (o0[2] * o0[2] + o0[3] * o0[3]) + (o1[0] * o1[0] + o1[1] * o1[1]) + (o1[2] * o1[2] + o1[3] * o1[3]);
;         ss += __shfl_xor(ss, 1); ss += __shfl_xor(ss, 2); ss += __shfl_xor(ss, 4); ss += __shfl_xor(ss, 8);
;         const float rr = rsqrtf(ss * (1.0f / 128.0f) + 1e-6f);
;         const int v0 = col & 127;
;         const f32x4 n0 = *(const f32x4*)(p.hg_nw + v0), n1 = *(const f32x4*)(p.hg_nw + v0 + 4);
;         const u32x4 gg = *(const u32x4*)(P + pix(tok, C_HG + col));
;         u32x4 wv;
;         wv.x = cvt_pk_bf16(o0[0] * rr * n0[0] * siluf_(bflo(gg.x)), o0[1] * rr * n0[1] * siluf_(bfhi(gg.x)));
;         wv.y = cvt_pk_bf16(o0[2] * rr * n0[2] * siluf_(bflo(gg.y)), o0[3] * rr * n0[3] * siluf_(bfhi(gg.y)));
;         wv.z = cvt_pk_bf16(o1[0] * rr * n1[0] * siluf_(bflo(gg.z)), o1[1] * rr * n1[1] * siluf_(bfhi(gg.z)));
;         wv.w = cvt_pk_bf16(o1[2] * rr * n1[2] * siluf_(bflo(gg.w)), o1[3] * rr * n1[3] * siluf_(bfhi(gg.w)));
;         *(u32x4*)(YB + (size_t)tok * 2048 + col) = wv;
.LBB0_646:
	s_cmp_lt_i32 s76, 5
	s_cselect_b64 s[6:7], -1, 0
	s_and_b64 s[6:7], s[6:7], s[4:5]
	s_andn2_b64 vcc, exec, s[6:7]
	s_cbranch_vccnz .LBB0_651
	s_waitcnt vmcnt(1)
	v_lshl_add_u32 v2, s2, 9, v196
	s_mov_b32 s4, 0x400000
	v_cmp_gt_i32_e32 vcc, s4, v2
	s_and_saveexec_b64 s[4:5], vcc
	s_cbranch_execz .LBB0_650
	v_mbcnt_lo_u32_b32 v0, -1, 0
	v_mbcnt_hi_u32_b32 v0, -1, v0
	v_and_b32_e32 v3, 64, v0
	v_xor_b32_e32 v1, 1, v0
	s_waitcnt vmcnt(0)
	v_add_u32_e32 v6, 64, v3
	v_cmp_lt_i32_e32 vcc, v1, v6
	s_add_u32 s8, s74, 0x52e00000
	s_addc_u32 s9, s75, 0
	v_cndmask_b32_e32 v1, v0, v1, vcc
	v_lshlrev_b32_e32 v3, 2, v1
	v_xor_b32_e32 v1, 2, v0
	v_cmp_lt_i32_e32 vcc, v1, v6
	s_lshl_b32 s12, s78, 9
	s_lshl_b32 s13, s78, 12
	v_cndmask_b32_e32 v1, v0, v1, vcc
	v_lshlrev_b32_e32 v4, 2, v1
	v_xor_b32_e32 v1, 4, v0
	v_cmp_lt_i32_e32 vcc, v1, v6
	s_mov_b64 s[10:11], 0
	v_mov_b32_e32 v8, 0x358637bd
	v_cndmask_b32_e32 v1, v0, v1, vcc
	v_lshlrev_b32_e32 v5, 2, v1
	v_xor_b32_e32 v1, 8, v0
	v_cmp_lt_i32_e32 vcc, v1, v6
	s_mov_b32 s14, 0x800000
	s_movk_i32 s15, 0x4200
	v_cndmask_b32_e32 v0, v0, v1, vcc
	v_lshlrev_b32_e32 v6, 2, v0
	v_lshlrev_b32_e32 v0, 3, v196
	v_lshl_add_u32 v7, s2, 12, v0
	v_mov_b32_e32 v1, 0
	v_mov_b32_e32 v61, 0
	v_mov_b32_e32 v9, 0x108000
	s_mov_b32 s16, 0x3fffff
.LBB0_649:
	v_ashrrev_i32_e32 v18, 8, v2
	v_lshlrev_b32_e32 v0, 7, v7
	v_and_b32_e32 v10, 0x78, v7
	v_and_b32_e32 v0, 0x3c000, v0
	v_ashrrev_i32_e32 v19, 31, v18
	v_lshlrev_b32_e32 v24, 2, v10
	v_lshl_add_u64 v[20:21], v[0:1], 0, v[18:19]
	v_or_b32_e32 v0, 0x40000, v0
	v_lshlrev_b32_e32 v22, 1, v10
	global_load_dwordx4 v[10:13], v24, s[44:45] offset:16
	global_load_dwordx4 v[14:17], v24, s[44:45]
	v_lshlrev_b64 v[24:25], 12, v[18:19]
	v_lshl_add_u64 v[26:27], v[0:1], 0, v[18:19]
	v_bfe_u32 v29, v7, 8, 3
	v_lshlrev_b64 v[20:21], 8, v[20:21]
	v_lshl_add_u64 v[30:31], s[8:9], 0, v[24:25]
	v_lshlrev_b64 v[24:25], 8, v[26:27]
	v_mov_b32_e32 v23, v1
	v_mad_u32_u24 v0, v29, s15, v9
	v_lshl_add_u64 v[20:21], s[74:75], 0, v[20:21]
	v_lshl_add_u64 v[24:25], s[74:75], 0, v[24:25]
	v_lshl_add_u64 v[18:19], v[0:1], 0, v[18:19]
	v_lshl_add_u64 v[20:21], v[20:21], 0, v[22:23]
	v_lshl_add_u64 v[22:23], v[24:25], 0, v[22:23]
	v_lshlrev_b64 v[26:27], 9, v[18:19]
	global_load_dwordx4 v[18:21], v[20:21], off
	v_and_b32_e32 v32, 0xf8, v7
	global_load_dwordx4 v[22:25], v[22:23], off
	v_lshlrev_b32_e32 v0, 1, v32
	v_lshl_add_u64 v[26:27], s[46:47], 0, v[26:27]
	v_and_b32_e32 v28, 0x7f8, v7
	v_lshl_add_u64 v[26:27], v[26:27], 0, v[0:1]
	v_lshlrev_b32_e32 v0, 1, v28
	global_load_dwordx4 v[26:29], v[26:27], off
	v_lshl_add_u64 v[30:31], v[30:31], 0, v[0:1]
	v_add_u32_e32 v2, s12, v2
	v_cmp_lt_i32_e32 vcc, s16, v2
	s_or_b64 s[10:11], vcc, s[10:11]
	v_add_u32_e32 v7, s13, v7
	v_ashrrev_i32_e32 v78, 8, v2
	v_lshlrev_b32_e32 v60, 7, v7
	v_and_b32_e32 v70, 0x78, v7
	v_and_b32_e32 v60, 0x3c000, v60
	v_ashrrev_i32_e32 v79, 31, v78
	v_lshlrev_b32_e32 v84, 2, v70
	v_lshl_add_u64 v[80:81], v[60:61], 0, v[78:79]
	v_or_b32_e32 v60, 0x40000, v60
	v_lshlrev_b32_e32 v82, 1, v70
	global_load_dwordx4 v[70:73], v84, s[44:45] offset:16
	global_load_dwordx4 v[74:77], v84, s[44:45]
	v_lshlrev_b64 v[84:85], 12, v[78:79]
	v_lshl_add_u64 v[86:87], v[60:61], 0, v[78:79]
	v_bfe_u32 v89, v7, 8, 3
	v_lshlrev_b64 v[80:81], 8, v[80:81]
	v_lshl_add_u64 v[90:91], s[8:9], 0, v[84:85]
	v_lshlrev_b64 v[84:85], 8, v[86:87]
	v_mov_b32_e32 v83, v61
	v_mad_u32_u24 v60, v89, s15, v9
	v_lshl_add_u64 v[80:81], s[74:75], 0, v[80:81]
	v_lshl_add_u64 v[84:85], s[74:75], 0, v[84:85]
	v_lshl_add_u64 v[78:79], v[60:61], 0, v[78:79]
	v_lshl_add_u64 v[80:81], v[80:81], 0, v[82:83]
	v_lshl_add_u64 v[82:83], v[84:85], 0, v[82:83]
	v_lshlrev_b64 v[86:87], 9, v[78:79]
	global_load_dwordx4 v[78:81], v[80:81], off
	v_and_b32_e32 v92, 0xf8, v7
	global_load_dwordx4 v[82:85], v[82:83], off
	v_lshlrev_b32_e32 v60, 1, v92
	v_lshl_add_u64 v[86:87], s[46:47], 0, v[86:87]
	v_and_b32_e32 v88, 0x7f8, v7
	v_lshl_add_u64 v[86:87], v[86:87], 0, v[60:61]
	v_lshlrev_b32_e32 v60, 1, v88
	global_load_dwordx4 v[86:89], v[86:87], off
	v_lshl_add_u64 v[90:91], v[90:91], 0, v[60:61]
	v_add_u32_e32 v2, s12, v2
	v_cmp_lt_i32_e32 vcc, s16, v2
	s_or_b64 s[10:11], vcc, s[10:11]
	v_add_u32_e32 v7, s13, v7
	s_waitcnt vmcnt(9)
	v_mov_b32_e32 v37, v10
	s_waitcnt vmcnt(8)
	v_mov_b32_e32 v33, v14
	v_mov_b32_e32 v39, v12
	v_mov_b32_e32 v35, v16
	s_waitcnt vmcnt(7)
	v_lshlrev_b32_e32 v40, 16, v18
	v_and_b32_e32 v18, 0xffff0000, v18
	v_lshlrev_b32_e32 v41, 16, v19
	v_and_b32_e32 v19, 0xffff0000, v19
	v_lshlrev_b32_e32 v43, 16, v20
	v_and_b32_e32 v45, 0xffff0000, v20
	v_lshlrev_b32_e32 v42, 16, v21
	v_and_b32_e32 v44, 0xffff0000, v21
	s_waitcnt vmcnt(6)
	v_lshlrev_b32_e32 v20, 16, v22
	v_and_b32_e32 v22, 0xffff0000, v22
	v_lshlrev_b32_e32 v21, 16, v23
	v_and_b32_e32 v23, 0xffff0000, v23
	v_and_b32_e32 v49, 0xffff0000, v24
	v_and_b32_e32 v48, 0xffff0000, v25
	v_pk_add_f32 v[18:19], v[18:19], v[22:23]
	v_lshlrev_b32_e32 v47, 16, v24
	v_lshlrev_b32_e32 v46, 16, v25
	v_pk_add_f32 v[20:21], v[40:41], v[20:21]
	v_pk_add_f32 v[24:25], v[44:45], v[48:49]
	v_pk_mul_f32 v[52:53], v[18:19], v[18:19]
	v_pk_add_f32 v[22:23], v[42:43], v[46:47]
	v_pk_mul_f32 v[54:55], v[24:25], v[24:25]
	v_pk_fma_f32 v[52:53], v[20:21], v[20:21], v[52:53]
	v_pk_fma_f32 v[54:55], v[22:23], v[22:23], v[54:55]
	v_add_f32_e32 v34, v52, v53
	s_waitcnt vmcnt(5)
; DI size_t oix(int dir, int tok, int h, int v) { return (((size_t)(dir * 16 + h)) * NLAT + (size_t)tok) * 128 + (size_t)v; }
; DI size_t pix(int row, int col) { return ((size_t)(col >> 8) * MROWS + (size_t)row) * 256 + (size_t)(col & 255); }
; DI float bflo(unsigned w) { return __uint_as_float(w << 16); }
; DI float bfhi(unsigned w) { return __uint_as_float(w & 0xffff0000u); }
; DI unsigned cvt_pk_bf16(float lo, float hi) { unsigned r; asm volatile("v_cvt_pk_bf16_f32 %0, %1, %2" : "=v"(r) : "v"(lo), "v"(hi)); return r; }
; DI float siluf_(float v) { return v * __builtin_amdgcn_rcpf(1.0f + __expf(-v)); }
; DI void phase_readout(const Params& p) {
;     ...
;         const int tok = idx >> 8, col = (idx & 255) * 8;
;         const u32x4 af = *(const u32x4*)(O + oix(0, tok, col >> 7, col & 127)), ab = *(const u32x4*)(O + oix(1, tok, col >> 7, col & 127));
;         const f32x4 o0 = (f32x4){bflo(af.x) + bflo(ab.x), bfhi(af.x) + bfhi(ab.x), bflo(af.y) + bflo(ab.y), bfhi(af.y) + bfhi(ab.y)};
;         const f32x4 o1 = (f32x4){bflo(af.z) + bflo(ab.z), bfhi(af.z) + bfhi(ab.z), bflo(af.w) + bflo(ab.w), bfhi(af.w) + bfhi(ab.w)};
;         float ss = (o0[0] * o0[0] + o0[1] * o0[1]) + (o0[2] * o0[2] + o0[3] * o0[3]) + (o1[0] * o1[0] + o1[1] * o1[1]) + (o1[2] * o1[2] + o1[3] * o1[3]);
;         ss += __shfl_xor(ss, 1); ss += __shfl_xor(ss, 2); ss += __shfl_xor(ss, 4); ss += __shfl_xor(ss, 8);
;         const float rr = rsqrtf(ss * (1.0f / 128.0f) + 1e-6f);
;         const int v0 = col & 127;
;         const f32x4 n0 = *(const f32x4*)(p.hg_nw + v0), n1 = *(const f32x4*)(p.hg_nw + v0 + 4);
;         const u32x4 gg = *(const u32x4*)(P + pix(tok, C_HG + col));
;         u32x4 wv;
;         wv.x = cvt_pk_bf16(o0[0] * rr * n0[0] * siluf_(bflo(gg.x)), o0[1] * rr * n0[1] * siluf_(bfhi(gg.x)));
;         wv.y = cvt_pk_bf16(o0[2] * rr * n0[2] * siluf_(bflo(gg.y)), o0[3] * rr * n0[3] * siluf_(bfhi(gg.y)));
;         wv.z = cvt_pk_bf16(o1[0] * rr * n1[0] * siluf_(bflo(gg.z)), o1[1] * rr * n1[1] * siluf_(bfhi(gg.z)));
;         wv.w = cvt_pk_bf16(o1[2] * rr * n1[2] * siluf_(bflo(gg.w)), o1[3] * rr * n1[3] * siluf_(bfhi(gg.w)));
;         *(u32x4*)(YB + (size_t)tok * 2048 + col) = wv;
	v_lshlrev_b32_e32 v40, 16, v26
	v_add_f32_e32 v34, v55, v34
	v_and_b32_e32 v26, 0xffff0000, v26
	v_lshlrev_b32_e32 v46, 16, v28
	v_and_b32_e32 v28, 0xffff0000, v28
	v_and_b32_e32 v50, 0xffff0000, v29
	v_mul_f32_e32 v0, 0xbfb8aa3b, v40
	v_add_f32_e32 v41, v54, v34
	v_lshlrev_b32_e32 v42, 16, v27
	v_and_b32_e32 v44, 0xffff0000, v27
	v_mul_f32_e32 v10, 0xbfb8aa3b, v26
	v_mul_f32_e32 v27, 0xbfb8aa3b, v28
	v_mul_f32_e32 v32, 0xbfb8aa3b, v50
	v_exp_f32_e32 v0, v0
	ds_bpermute_b32 v43, v3, v41
	v_mul_f32_e32 v14, 0xbfb8aa3b, v44
	v_exp_f32_e32 v10, v10
	v_exp_f32_e32 v27, v27
	v_exp_f32_e32 v32, v32
	v_exp_f32_e32 v14, v14
	v_add_f32_e32 v0, 1.0, v0
	v_add_f32_e32 v10, 1.0, v10
	v_add_f32_e32 v27, 1.0, v27
	v_add_f32_e32 v45, 1.0, v32
	v_rcp_f32_e32 v32, v0
	s_waitcnt lgkmcnt(0)
	v_add_f32_e32 v0, v41, v43
	v_add_f32_e32 v36, 1.0, v14
	v_rcp_f32_e32 v14, v10
	v_rcp_f32_e32 v10, v27
	ds_bpermute_b32 v27, v4, v0
	v_lshlrev_b32_e32 v48, 16, v29
	v_mul_f32_e32 v12, 0xbfb8aa3b, v42
	v_mul_f32_e32 v16, 0xbfb8aa3b, v46
	v_mul_f32_e32 v29, 0xbfb8aa3b, v48
	s_waitcnt lgkmcnt(0)
	v_add_f32_e32 v0, v0, v27
	ds_bpermute_b32 v27, v5, v0
	v_exp_f32_e32 v12, v12
	v_exp_f32_e32 v16, v16
	v_exp_f32_e32 v29, v29
	s_waitcnt lgkmcnt(0)
	v_add_f32_e32 v0, v0, v27
	ds_bpermute_b32 v27, v6, v0
	v_add_f32_e32 v12, 1.0, v12
	v_add_f32_e32 v38, 1.0, v16
	v_add_f32_e32 v29, 1.0, v29
	v_rcp_f32_e32 v34, v12
	s_waitcnt lgkmcnt(0)
	v_add_f32_e32 v0, v0, v27
	v_fmamk_f32 v0, v0, 0x3c000000, v8
	v_mul_f32_e32 v27, 0x4b800000, v0
	v_cmp_gt_f32_e32 vcc, s14, v0
	v_rcp_f32_e32 v12, v45
	v_rcp_f32_e32 v16, v36
	v_cndmask_b32_e32 v0, v0, v27, vcc
	v_rsq_f32_e32 v0, v0
	v_rcp_f32_e32 v36, v38
	v_rcp_f32_e32 v38, v29
	v_mul_f32_e32 v27, 0x45800000, v0
	v_cndmask_b32_e32 v0, v0, v27, vcc
	v_mul_f32_e32 v51, v24, v0
	v_mul_f32_e32 v41, v20, v0
	v_mul_f32_e32 v27, v18, v0
	v_mul_f32_e32 v43, v21, v0
	v_mul_f32_e32 v45, v19, v0
	v_mul_f32_e32 v47, v23, v0
	v_mul_f32_e32 v29, v25, v0
	v_mul_f32_e32 v49, v22, v0
	v_pk_mul_f32 v[12:13], v[12:13], v[50:51]
	v_pk_mul_f32 v[18:19], v[32:33], v[40:41]
	v_pk_mul_f32 v[14:15], v[14:15], v[26:27]
	v_pk_mul_f32 v[20:21], v[34:35], v[42:43]
	v_pk_mul_f32 v[16:17], v[16:17], v[44:45]
	v_pk_mul_f32 v[22:23], v[36:37], v[46:47]
	v_pk_mul_f32 v[10:11], v[10:11], v[28:29]
	v_pk_mul_f32 v[24:25], v[38:39], v[48:49]
	v_mul_f32_e32 v13, v12, v13
	v_mul_f32_e32 v0, v18, v19
	v_mul_f32_e32 v14, v14, v15
	v_mul_f32_e32 v15, v20, v21
	v_mul_f32_e32 v16, v16, v17
	v_mul_f32_e32 v17, v22, v23
	v_mul_f32_e32 v18, v10, v11
	v_mul_f32_e32 v19, v24, v25
	v_cvt_pk_bf16_f32 v10, v0, v14
	v_cvt_pk_bf16_f32 v11, v15, v16
	v_cvt_pk_bf16_f32 v12, v17, v18
	v_cvt_pk_bf16_f32 v13, v19, v13
	global_store_dwordx4 v[30:31], v[10:13], off
	s_waitcnt vmcnt(5)
	v_mov_b32_e32 v97, v70
	s_waitcnt vmcnt(4)
	v_mov_b32_e32 v93, v74
	v_mov_b32_e32 v99, v72
	v_mov_b32_e32 v95, v76
	s_waitcnt vmcnt(3)
	v_lshlrev_b32_e32 v100, 16, v78
	v_and_b32_e32 v78, 0xffff0000, v78
	v_lshlrev_b32_e32 v101, 16, v79
	v_and_b32_e32 v79, 0xffff0000, v79
	v_lshlrev_b32_e32 v103, 16, v80
	v_and_b32_e32 v105, 0xffff0000, v80
	v_lshlrev_b32_e32 v102, 16, v81
	v_and_b32_e32 v104, 0xffff0000, v81
	s_waitcnt vmcnt(2)
	v_lshlrev_b32_e32 v80, 16, v82
	v_and_b32_e32 v82, 0xffff0000, v82
	v_lshlrev_b32_e32 v81, 16, v83
	v_and_b32_e32 v83, 0xffff0000, v83
	v_and_b32_e32 v109, 0xffff0000, v84
	v_and_b32_e32 v108, 0xffff0000, v85
	v_pk_add_f32 v[78:79], v[78:79], v[82:83]
	v_lshlrev_b32_e32 v107, 16, v84
	v_lshlrev_b32_e32 v106, 16, v85
	v_pk_add_f32 v[80:81], v[100:101], v[80:81]
	v_pk_add_f32 v[84:85], v[104:105], v[108:109]
	v_pk_mul_f32 v[112:113], v[78:79], v[78:79]
	v_pk_add_f32 v[82:83], v[102:103], v[106:107]
	v_pk_mul_f32 v[114:115], v[84:85], v[84:85]
	v_pk_fma_f32 v[112:113], v[80:81], v[80:81], v[112:113]
	v_pk_fma_f32 v[114:115], v[82:83], v[82:83], v[114:115]
	v_add_f32_e32 v94, v112, v113
	s_waitcnt vmcnt(1)
	v_lshlrev_b32_e32 v100, 16, v86
	v_add_f32_e32 v94, v115, v94
	v_and_b32_e32 v86, 0xffff0000, v86
	v_lshlrev_b32_e32 v106, 16, v88
	v_and_b32_e32 v88, 0xffff0000, v88
	v_and_b32_e32 v110, 0xffff0000, v89
	v_mul_f32_e32 v60, 0xbfb8aa3b, v100
	v_add_f32_e32 v101, v114, v94
	v_lshlrev_b32_e32 v102, 16, v87
	v_and_b32_e32 v104, 0xffff0000, v87
	v_mul_f32_e32 v70, 0xbfb8aa3b, v86
	v_mul_f32_e32 v87, 0xbfb8aa3b, v88
	v_mul_f32_e32 v92, 0xbfb8aa3b, v110
	v_exp_f32_e32 v60, v60
	ds_bpermute_b32 v103, v3, v101
	v_mul_f32_e32 v74, 0xbfb8aa3b, v104
	v_exp_f32_e32 v70, v70
	v_exp_f32_e32 v87, v87
	v_exp_f32_e32 v92, v92
	v_exp_f32_e32 v74, v74
	v_add_f32_e32 v60, 1.0, v60
	v_add_f32_e32 v70, 1.0, v70
	v_add_f32_e32 v87, 1.0, v87
	v_add_f32_e32 v105, 1.0, v92
	v_rcp_f32_e32 v92, v60
	s_waitcnt lgkmcnt(0)
	v_add_f32_e32 v60, v101, v103
	v_add_f32_e32 v96, 1.0, v74
	v_rcp_f32_e32 v74, v70
	v_rcp_f32_e32 v70, v87
	ds_bpermute_b32 v87, v4, v60
	v_lshlrev_b32_e32 v108, 16, v89
	v_mul_f32_e32 v72, 0xbfb8aa3b, v102
	v_mul_f32_e32 v76, 0xbfb8aa3b, v106
	v_mul_f32_e32 v89, 0xbfb8aa3b, v108
	s_waitcnt lgkmcnt(0)
	v_add_f32_e32 v60, v60, v87
	ds_bpermute_b32 v87, v5, v60
	v_exp_f32_e32 v72, v72
	v_exp_f32_e32 v76, v76
	v_exp_f32_e32 v89, v89
	s_waitcnt lgkmcnt(0)
	v_add_f32_e32 v60, v60, v87
	ds_bpermute_b32 v87, v6, v60
	v_add_f32_e32 v72, 1.0, v72
	v_add_f32_e32 v98, 1.0, v76
	v_add_f32_e32 v89, 1.0, v89
	v_rcp_f32_e32 v94, v72
	s_waitcnt lgkmcnt(0)
	v_add_f32_e32 v60, v60, v87
	v_fmamk_f32 v60, v60, 0x3c000000, v8
	v_mul_f32_e32 v87, 0x4b800000, v60
	v_cmp_gt_f32_e32 vcc, s14, v60
	v_rcp_f32_e32 v72, v105
	v_rcp_f32_e32 v76, v96
	v_cndmask_b32_e32 v60, v60, v87, vcc
	v_rsq_f32_e32 v60, v60
	v_rcp_f32_e32 v96, v98
	v_rcp_f32_e32 v98, v89
	v_mul_f32_e32 v87, 0x45800000, v60
	v_cndmask_b32_e32 v60, v60, v87, vcc
	v_mul_f32_e32 v111, v84, v60
	v_mul_f32_e32 v101, v80, v60
	v_mul_f32_e32 v87, v78, v60
	v_mul_f32_e32 v103, v81, v60
	v_mul_f32_e32 v105, v79, v60
	v_mul_f32_e32 v107, v83, v60
	v_mul_f32_e32 v89, v85, v60
	v_mul_f32_e32 v109, v82, v60
	v_pk_mul_f32 v[72:73], v[72:73], v[110:111]
	v_pk_mul_f32 v[78:79], v[92:93], v[100:101]
	v_pk_mul_f32 v[74:75], v[74:75], v[86:87]
	v_pk_mul_f32 v[80:81], v[94:95], v[102:103]
	v_pk_mul_f32 v[76:77], v[76:77], v[104:105]
	v_pk_mul_f32 v[82:83], v[96:97], v[106:107]
	v_pk_mul_f32 v[70:71], v[70:71], v[88:89]
	v_pk_mul_f32 v[84:85], v[98:99], v[108:109]
	v_mul_f32_e32 v73, v72, v73
	v_mul_f32_e32 v60, v78, v79
	v_mul_f32_e32 v74, v74, v75
	v_mul_f32_e32 v75, v80, v81
	v_mul_f32_e32 v76, v76, v77
	v_mul_f32_e32 v77, v82, v83
	v_mul_f32_e32 v78, v70, v71
	v_mul_f32_e32 v79, v84, v85
	v_cvt_pk_bf16_f32 v70, v60, v74
	v_cvt_pk_bf16_f32 v71, v75, v76
	v_cvt_pk_bf16_f32 v72, v77, v78
	v_cvt_pk_bf16_f32 v73, v79, v73
	global_store_dwordx4 v[90:91], v[70:73], off
	s_andn2_b64 exec, exec, s[10:11]
	s_cbranch_execnz .LBB0_649
